# sink the P1..P3 lane-half swaps from the MFMA-free QK-to-PV stretch into the shadows of PV slots 0..2
# speedup vs baseline: 1.0010x; 1.0010x over previous
.LBB0_1096:
	ds_read_b128 v[64:67], v194 offset:49152
	ds_read_b128 v[68:71], v195 offset:57344
	ds_read_b128 v[214:217], v196 offset:49152
	ds_read_b128 v[224:227], v197 offset:57344
	v_add_f32_e32 v160, 0, v175
	v_add_f32_e32 v160, v223, v160
	s_waitcnt lgkmcnt(3)
	v_mfma_f32_32x32x16_bf16 v[80:95], v[64:67], v[100:103], 0
	v_add_f32_e32 v160, v161, v160
	v_add_f32_e32 v160, v220, v160
	v_add_f32_e32 v160, v162, v160
	v_add_f32_e32 v160, v174, v160
	v_add_f32_e32 v160, v163, v160
	v_add_f32_e32 v160, v173, v160
	v_add_f32_e32 v160, v164, v160
	s_waitcnt lgkmcnt(2)
	v_mfma_f32_32x32x16_bf16 v[64:79], v[68:71], v[100:103], 0
	v_add_f32_e32 v160, v172, v160
	v_add_f32_e32 v160, v165, v160
	v_add_f32_e32 v160, v171, v160
	v_exp_f32_e32 v156, v156
	v_add_f32_e32 v160, v166, v160
	v_exp_f32_e32 v157, v157
	v_add_f32_e32 v160, v170, v160
	s_waitcnt lgkmcnt(1)
	v_mfma_f32_32x32x16_bf16 v[80:95], v[214:217], v[108:111], v[80:95]
	v_exp_f32_e32 v154, v154
	v_add_f32_e32 v160, v167, v160
	v_exp_f32_e32 v155, v155
	v_add_f32_e32 v160, v169, v160
	v_exp_f32_e32 v148, v148
	v_add_f32_e32 v160, v156, v160
	v_exp_f32_e32 v149, v149
	s_waitcnt lgkmcnt(0)
	v_mfma_f32_32x32x16_bf16 v[64:79], v[224:227], v[108:111], v[64:79]
	ds_read_b128 v[214:217], v198 offset:49152
	ds_read_b128 v[224:227], v200 offset:57344
	v_add_f32_e32 v160, v157, v160
	v_exp_f32_e32 v146, v146
	v_add_f32_e32 v160, v154, v160
	v_exp_f32_e32 v147, v147
	v_add_f32_e32 v160, v155, v160
	v_exp_f32_e32 v144, v144
	s_waitcnt lgkmcnt(1)
	v_mfma_f32_32x32x16_bf16 v[80:95], v[214:217], v[96:99], v[80:95]
	v_add_f32_e32 v160, v148, v160
	v_exp_f32_e32 v145, v145
	v_add_f32_e32 v160, v149, v160
	v_exp_f32_e32 v158, v158
	v_add_f32_e32 v160, v146, v160
	v_exp_f32_e32 v159, v159
	v_add_f32_e32 v160, v147, v160
	s_waitcnt lgkmcnt(0)
	v_mfma_f32_32x32x16_bf16 v[64:79], v[224:227], v[96:99], v[64:79]
	ds_read_b128 v[214:217], v199 offset:49152
	ds_read_b128 v[224:227], v201 offset:57344
	v_exp_f32_e32 v152, v152
	v_add_f32_e32 v160, v144, v160
	v_exp_f32_e32 v153, v153
	v_add_f32_e32 v160, v145, v160
	v_exp_f32_e32 v150, v150
	v_add_f32_e32 v160, v158, v160
	s_waitcnt lgkmcnt(1)
	v_mfma_f32_32x32x16_bf16 v[80:95], v[214:217], v[104:107], v[80:95]
	v_exp_f32_e32 v151, v151
	v_add_f32_e32 v160, v159, v160
	v_add_f32_e32 v160, v152, v160
	v_add_f32_e32 v160, v153, v160
	v_add_f32_e32 v160, v150, v160
	v_add_f32_e32 v211, v151, v160
	v_mov_b32_e32 v218, v211
	s_waitcnt lgkmcnt(0)
	v_mfma_f32_32x32x16_bf16 v[64:79], v[224:227], v[104:107], v[64:79]
	ds_read_b128 v[214:217], v202 offset:49152
	ds_read_b128 v[224:227], v203 offset:57344
	v_permlane32_swap_b32_e32 v211, v218
	s_waitcnt lgkmcnt(1)
	v_mfma_f32_32x32x16_bf16 v[80:95], v[214:217], v[116:119], v[80:95]
	s_waitcnt lgkmcnt(0)
	v_mfma_f32_32x32x16_bf16 v[64:79], v[224:227], v[116:119], v[64:79]
	ds_read_b128 v[214:217], v204 offset:49152
	ds_read_b128 v[224:227], v205 offset:57344
	s_waitcnt lgkmcnt(1)
	v_mfma_f32_32x32x16_bf16 v[80:95], v[214:217], v[124:127], v[80:95]
	s_waitcnt lgkmcnt(0)
	v_mfma_f32_32x32x16_bf16 v[64:79], v[224:227], v[124:127], v[64:79]
	ds_read_b128 v[214:217], v206 offset:49152
	ds_read_b128 v[224:227], v208 offset:57344
	s_waitcnt lgkmcnt(1)
	v_mfma_f32_32x32x16_bf16 v[80:95], v[214:217], v[112:115], v[80:95]
	s_waitcnt lgkmcnt(0)
	v_mfma_f32_32x32x16_bf16 v[64:79], v[224:227], v[112:115], v[64:79]
	ds_read_b128 v[214:217], v207 offset:49152
	ds_read_b128 v[224:227], v209 offset:57344
	v_cvt_pk_bf16_f32 v160, v175, v223
	v_cvt_pk_bf16_f32 v161, v161, v220
	v_cvt_pk_bf16_f32 v162, v162, v174
	v_cvt_pk_bf16_f32 v163, v163, v173
	v_cvt_pk_bf16_f32 v164, v164, v172
	v_cvt_pk_bf16_f32 v165, v165, v171
	s_waitcnt lgkmcnt(1)
	v_mfma_f32_32x32x16_bf16 v[80:95], v[214:217], v[120:123], v[80:95]
	v_permlane32_swap_b32_e32 v160, v162
	v_cvt_pk_bf16_f32 v166, v166, v170
	v_cvt_pk_bf16_f32 v167, v167, v169
	v_cvt_pk_bf16_f32 v170, v156, v157
	v_cvt_pk_bf16_f32 v171, v154, v155
	v_cvt_pk_bf16_f32 v172, v148, v149
	s_waitcnt lgkmcnt(0)
	v_mfma_f32_32x32x16_bf16 v[64:79], v[224:227], v[120:123], v[64:79]
	v_cvt_pk_bf16_f32 v173, v146, v147
	v_cvt_pk_bf16_f32 v214, v144, v145
	v_cvt_pk_bf16_f32 v215, v158, v159
	v_cvt_pk_bf16_f32 v216, v152, v153
	v_cvt_pk_bf16_f32 v217, v150, v151
	v_permlane32_swap_b32_e32 v161, v163
	v_lshl_add_u64 v[144:145], v[180:181], 0, s[8:9]
	s_mov_b32 s2, 0x322f0000
	v_add_co_u32_e32 v146, vcc, s2, v144
	s_mov_b32 s2, 0x32318000
	s_nop 0
	v_addc_co_u32_e32 v147, vcc, 0, v145, vcc
	v_add_co_u32_e32 v148, vcc, s2, v144
	v_lshl_add_u64 v[152:153], v[178:179], 0, s[8:9]
	s_nop 0
	v_addc_co_u32_e32 v149, vcc, 0, v145, vcc
	s_mov_b32 s2, 0x41018000
	v_add_co_u32_e32 v154, vcc, s2, v152
	s_mov_b32 s2, 0x4101c000
	s_nop 0
	v_addc_co_u32_e32 v155, vcc, 0, v153, vcc
	v_add_co_u32_e32 v156, vcc, s2, v152
	global_load_dwordx4 v[144:147], v[146:147], off offset:2560
	s_nop 0
	global_load_dwordx4 v[148:151], v[148:149], off offset:2560
	v_addc_co_u32_e32 v157, vcc, 0, v153, vcc
	global_load_dwordx4 v[152:155], v[154:155], off
	s_nop 0
	global_load_dwordx4 v[156:159], v[156:157], off
	ds_read_b64_tr_b16 v[220:221], v189 offset:0
	ds_read_b64_tr_b16 v[222:223], v189 offset:0x800
	ds_read_b64_tr_b16 v[224:225], v189 offset:0x200
	ds_read_b64_tr_b16 v[226:227], v189 offset:0xa00
	ds_read_b64_tr_b16 v[230:231], v189 offset:0x400
	ds_read_b64_tr_b16 v[232:233], v189 offset:0xc00
	ds_read_b64_tr_b16 v[238:239], v189 offset:0x600
	ds_read_b64_tr_b16 v[240:241], v189 offset:0xe00
	s_waitcnt lgkmcnt(6)
	s_nop 0
	v_mfma_f32_32x32x16_bf16 v[0:15], v[160:163], v[220:223], v[0:15]
	ds_read_b64_tr_b16 v[220:221], v189 offset:0x1000
	ds_read_b64_tr_b16 v[222:223], v189 offset:0x1800
	v_permlane32_swap_b32_e32 v164, v166
	v_permlane32_swap_b32_e32 v165, v167
	s_waitcnt lgkmcnt(6)
	v_mfma_f32_32x32x16_bf16 v[48:63], v[160:163], v[224:227], v[48:63]
	ds_read_b64_tr_b16 v[224:225], v189 offset:0x1200
	ds_read_b64_tr_b16 v[226:227], v189 offset:0x1a00
	v_permlane32_swap_b32_e32 v170, v172
	v_permlane32_swap_b32_e32 v171, v173
	s_waitcnt lgkmcnt(6)
	v_mfma_f32_32x32x16_bf16 v[32:47], v[160:163], v[230:233], v[32:47]
	ds_read_b64_tr_b16 v[230:231], v189 offset:0x1400
	ds_read_b64_tr_b16 v[232:233], v189 offset:0x1c00
	v_permlane32_swap_b32_e32 v214, v216
	v_permlane32_swap_b32_e32 v215, v217
	s_waitcnt lgkmcnt(6)
	v_mfma_f32_32x32x16_bf16 v[16:31], v[160:163], v[238:241], v[16:31]
	ds_read_b64_tr_b16 v[238:239], v189 offset:0x1600
	ds_read_b64_tr_b16 v[240:241], v189 offset:0x1e00
	s_waitcnt lgkmcnt(6)
	v_mfma_f32_32x32x16_bf16 v[0:15], v[164:167], v[220:223], v[0:15]
	ds_read_b64_tr_b16 v[220:221], v189 offset:0x2000
	ds_read_b64_tr_b16 v[222:223], v189 offset:0x2800
	v_max_f32_e32 v160, v81, v81
	v_max_f32_e32 v161, v80, v80
	v_max_f32_e32 v160, v161, v160
	v_max3_f32 v160, v160, v82, v83
	v_max3_f32 v160, v160, v84, v85
	v_max3_f32 v160, v160, v86, v87
	v_max3_f32 v160, v160, v88, v89
	v_max3_f32 v160, v160, v90, v91
	s_waitcnt lgkmcnt(6)
	v_mfma_f32_32x32x16_bf16 v[48:63], v[164:167], v[224:227], v[48:63]
	ds_read_b64_tr_b16 v[224:225], v189 offset:0x2200
	ds_read_b64_tr_b16 v[226:227], v189 offset:0x2a00
	s_waitcnt lgkmcnt(6)
	v_mfma_f32_32x32x16_bf16 v[32:47], v[164:167], v[230:233], v[32:47]
	ds_read_b64_tr_b16 v[230:231], v189 offset:0x2400
	ds_read_b64_tr_b16 v[232:233], v189 offset:0x2c00
	v_max3_f32 v160, v160, v92, v93
	v_max3_f32 v160, v160, v94, v95
	v_max3_f32 v160, v160, v64, v65
	v_max3_f32 v160, v160, v66, v67
	v_max3_f32 v160, v160, v68, v69
	v_max3_f32 v160, v160, v70, v71
	v_max3_f32 v160, v160, v72, v73
	v_max3_f32 v160, v160, v74, v75
	s_waitcnt lgkmcnt(6)
	v_mfma_f32_32x32x16_bf16 v[16:31], v[164:167], v[238:241], v[16:31]
	ds_read_b64_tr_b16 v[238:239], v189 offset:0x2600
	ds_read_b64_tr_b16 v[240:241], v189 offset:0x2e00
	s_waitcnt lgkmcnt(6)
	v_mfma_f32_32x32x16_bf16 v[0:15], v[170:173], v[220:223], v[0:15]
	ds_read_b64_tr_b16 v[220:221], v189 offset:0x3000
	ds_read_b64_tr_b16 v[222:223], v189 offset:0x3800
	v_max3_f32 v160, v160, v76, v77
	v_max3_f32 v160, v160, v78, v79
	v_mov_b32_e32 v161, v160
	s_nop 1
	v_permlane32_swap_b32_e32 v160, v161
	v_max_f32_e32 v161, v161, v161
	v_max_f32_e32 v160, v160, v160
	v_max_f32_e32 v160, v160, v161
	s_waitcnt lgkmcnt(6)
	v_mfma_f32_32x32x16_bf16 v[48:63], v[170:173], v[224:227], v[48:63]
	ds_read_b64_tr_b16 v[224:225], v189 offset:0x3200
	ds_read_b64_tr_b16 v[226:227], v189 offset:0x3a00
	s_waitcnt lgkmcnt(6)
	v_mfma_f32_32x32x16_bf16 v[32:47], v[170:173], v[230:233], v[32:47]
	ds_read_b64_tr_b16 v[230:231], v189 offset:0x3400
	ds_read_b64_tr_b16 v[232:233], v189 offset:0x3c00
	v_sub_f32_e32 v161, v160, v168
	v_cmp_ge_f32_e32 vcc, s90, v161
	v_max_f32_e32 v161, v168, v168
	v_max_f32_e32 v160, v161, v160
	v_sub_f32_e32 v161, v168, v160
	v_mul_f32_e32 v161, 0x3e0293ee, v161
	v_exp_f32_e32 v161, v161
	s_cmp_eq_u64 vcc, exec
	s_cselect_b64 s[38:39], -1, 0
	s_waitcnt lgkmcnt(6)
	v_mfma_f32_32x32x16_bf16 v[16:31], v[170:173], v[238:241], v[16:31]
	ds_read_b64_tr_b16 v[238:239], v189 offset:0x3600
	ds_read_b64_tr_b16 v[240:241], v189 offset:0x3e00
	s_waitcnt lgkmcnt(6)
	v_mfma_f32_32x32x16_bf16 v[0:15], v[214:217], v[220:223], v[0:15]
	s_waitcnt lgkmcnt(0)
	s_barrier
	v_mfma_f32_32x32x16_bf16 v[48:63], v[214:217], v[224:227], v[48:63]
	s_waitcnt vmcnt(4)
	v_cndmask_b32_e64 v219, v161, 1.0, s[38:39]
	v_cmp_gt_f32_e32 vcc, 1.0, v219
	s_waitcnt vmcnt(7)
	ds_write_b128 v190, v[128:131]
	s_waitcnt vmcnt(6)
	ds_write_b128 v191, v[132:135]
	v_mfma_f32_32x32x16_bf16 v[32:47], v[214:217], v[230:233], v[32:47]
	s_waitcnt vmcnt(5)
	ds_write_b128 v192, v[136:139] offset:32768
	s_waitcnt vmcnt(4)
	ds_write_b128 v193, v[140:143] offset:32768
	v_mfma_f32_32x32x16_bf16 v[16:31], v[214:217], v[238:241], v[16:31]
	s_cbranch_vccz .LBB0_1100
	s_and_saveexec_b64 s[2:3], s[36:37]
	ds_write_b32 v186, v219 offset:128
	s_or_b64 exec, exec, s[2:3]
	s_waitcnt lgkmcnt(0)
	v_add_u32_e32 v161, s27, v185
	ds_read_b128 v[162:165], v161 offset:224
	ds_read_b128 v[170:173], v161 offset:192
	ds_read_b128 v[214:217], v161 offset:160
	ds_read_b128 v[220:223], v161 offset:128
	s_waitcnt lgkmcnt(3)
	v_pk_mul_f32 v[12:13], v[12:13], v[162:163]
	s_waitcnt lgkmcnt(2)
	v_pk_mul_f32 v[8:9], v[8:9], v[170:171]
	s_waitcnt lgkmcnt(1)
	v_pk_mul_f32 v[4:5], v[4:5], v[214:215]
	v_pk_mul_f32 v[14:15], v[14:15], v[164:165]
	v_pk_mul_f32 v[10:11], v[10:11], v[172:173]
	v_pk_mul_f32 v[6:7], v[6:7], v[216:217]
	s_waitcnt lgkmcnt(0)
	v_pk_mul_f32 v[2:3], v[2:3], v[222:223]
	v_pk_mul_f32 v[0:1], v[0:1], v[220:221]
	v_pk_mul_f32 v[60:61], v[60:61], v[162:163]
	v_pk_mul_f32 v[56:57], v[56:57], v[170:171]
	v_pk_mul_f32 v[52:53], v[52:53], v[214:215]
	v_pk_mul_f32 v[62:63], v[62:63], v[164:165]
	v_pk_mul_f32 v[58:59], v[58:59], v[172:173]
	v_pk_mul_f32 v[54:55], v[54:55], v[216:217]
	v_pk_mul_f32 v[50:51], v[50:51], v[222:223]
	v_pk_mul_f32 v[48:49], v[48:49], v[220:221]
	v_pk_mul_f32 v[44:45], v[44:45], v[162:163]
	v_pk_mul_f32 v[40:41], v[40:41], v[170:171]
	v_pk_mul_f32 v[36:37], v[36:37], v[214:215]
	v_pk_mul_f32 v[46:47], v[46:47], v[164:165]
	v_pk_mul_f32 v[42:43], v[42:43], v[172:173]
	v_pk_mul_f32 v[38:39], v[38:39], v[216:217]
	v_pk_mul_f32 v[34:35], v[34:35], v[222:223]
	v_pk_mul_f32 v[32:33], v[32:33], v[220:221]
	v_pk_mul_f32 v[28:29], v[28:29], v[162:163]
	v_pk_mul_f32 v[24:25], v[24:25], v[170:171]
	v_pk_mul_f32 v[20:21], v[20:21], v[214:215]
	v_pk_mul_f32 v[30:31], v[30:31], v[164:165]
	v_pk_mul_f32 v[26:27], v[26:27], v[172:173]
	v_pk_mul_f32 v[22:23], v[22:23], v[216:217]
	v_pk_mul_f32 v[18:19], v[18:19], v[222:223]
	v_pk_mul_f32 v[16:17], v[16:17], v[220:221]
.LBB0_1100:
	v_cndmask_b32_e64 v220, v160, v168, s[38:39]
	v_mul_f32_e32 v221, 0xbe0293ee, v220
	v_fmamk_f32 v80, v80, 0x3e0293ee, v221
	v_fmamk_f32 v81, v81, 0x3e0293ee, v221
	v_fmamk_f32 v82, v82, 0x3e0293ee, v221
	v_fmamk_f32 v83, v83, 0x3e0293ee, v221
	v_fmamk_f32 v84, v84, 0x3e0293ee, v221
	v_fmamk_f32 v85, v85, 0x3e0293ee, v221
	v_fmamk_f32 v86, v86, 0x3e0293ee, v221
	v_fmamk_f32 v87, v87, 0x3e0293ee, v221
	v_fmamk_f32 v88, v88, 0x3e0293ee, v221
	v_fmamk_f32 v89, v89, 0x3e0293ee, v221
	v_fmamk_f32 v90, v90, 0x3e0293ee, v221
	v_fmamk_f32 v91, v91, 0x3e0293ee, v221
	v_fmamk_f32 v92, v92, 0x3e0293ee, v221
	v_fmamk_f32 v93, v93, 0x3e0293ee, v221
	v_fmamk_f32 v94, v94, 0x3e0293ee, v221
	v_fmamk_f32 v95, v95, 0x3e0293ee, v221
	v_exp_f32_e32 v160, v80
	v_exp_f32_e32 v175, v81
	v_exp_f32_e32 v161, v82
	v_exp_f32_e32 v174, v83
	v_exp_f32_e32 v162, v84
	v_exp_f32_e32 v173, v85
	v_exp_f32_e32 v163, v86
	v_exp_f32_e32 v172, v87
	v_exp_f32_e32 v164, v88
	v_exp_f32_e32 v171, v89
	v_exp_f32_e32 v165, v90
	v_exp_f32_e32 v170, v91
	v_exp_f32_e32 v166, v92
	v_exp_f32_e32 v169, v93
	v_exp_f32_e32 v167, v94
	v_exp_f32_e32 v168, v95
	v_fmamk_f32 v240, v64, 0x3e0293ee, v221
	v_fmamk_f32 v241, v65, 0x3e0293ee, v221
	v_fmamk_f32 v242, v66, 0x3e0293ee, v221
	v_fmamk_f32 v243, v67, 0x3e0293ee, v221
	v_fmamk_f32 v244, v68, 0x3e0293ee, v221
	v_fmamk_f32 v223, v69, 0x3e0293ee, v221
	v_fmamk_f32 v224, v70, 0x3e0293ee, v221
	v_fmamk_f32 v225, v71, 0x3e0293ee, v221
	v_fmamk_f32 v226, v72, 0x3e0293ee, v221
	v_fmamk_f32 v227, v73, 0x3e0293ee, v221
	v_fmamk_f32 v238, v74, 0x3e0293ee, v221
	v_fmamk_f32 v239, v75, 0x3e0293ee, v221
	v_fmamk_f32 v222, v76, 0x3e0293ee, v221
	v_fmamk_f32 v245, v77, 0x3e0293ee, v221
	v_fmamk_f32 v246, v78, 0x3e0293ee, v221
	v_fmac_f32_e32 v221, 0x3e0293ee, v79
	s_waitcnt lgkmcnt(0)
	s_barrier
	ds_read_b128 v[64:67], v194 offset:32768
	ds_read_b128 v[68:71], v195 offset:40960
	ds_read_b128 v[214:217], v196 offset:32768
	ds_read_b128 v[230:233], v197 offset:40960
	v_exp_f32_e32 v223, v223
	v_exp_f32_e32 v224, v224
	s_waitcnt lgkmcnt(3)
	v_mfma_f32_32x32x16_bf16 v[80:95], v[64:67], v[100:103], 0
	v_exp_f32_e32 v225, v225
	v_exp_f32_e32 v226, v226
	v_exp_f32_e32 v227, v227
	v_exp_f32_e32 v234, v245
	v_exp_f32_e32 v235, v246
	s_waitcnt lgkmcnt(2)
	v_mfma_f32_32x32x16_bf16 v[64:79], v[68:71], v[100:103], 0
	s_waitcnt lgkmcnt(0)
	v_mfma_f32_32x32x16_bf16 v[64:79], v[230:233], v[108:111], v[64:79]
	v_mfma_f32_32x32x16_bf16 v[80:95], v[214:217], v[108:111], v[80:95]
	ds_read_b128 v[214:217], v198 offset:32768
	ds_read_b128 v[230:233], v200 offset:40960
	s_waitcnt lgkmcnt(0)
	v_mfma_f32_32x32x16_bf16 v[64:79], v[230:233], v[96:99], v[64:79]
	v_mfma_f32_32x32x16_bf16 v[80:95], v[214:217], v[96:99], v[80:95]
	ds_read_b128 v[214:217], v199 offset:32768
	ds_read_b128 v[230:233], v201 offset:40960
	s_waitcnt lgkmcnt(0)
	v_mfma_f32_32x32x16_bf16 v[64:79], v[230:233], v[104:107], v[64:79]
	v_mfma_f32_32x32x16_bf16 v[80:95], v[214:217], v[104:107], v[80:95]
	ds_read_b128 v[214:217], v202 offset:32768
	ds_read_b128 v[230:233], v203 offset:40960
	s_waitcnt lgkmcnt(0)
	v_mfma_f32_32x32x16_bf16 v[64:79], v[230:233], v[116:119], v[64:79]
	v_mfma_f32_32x32x16_bf16 v[80:95], v[214:217], v[116:119], v[80:95]
	ds_read_b128 v[214:217], v204 offset:32768
	ds_read_b128 v[230:233], v205 offset:40960
	s_waitcnt lgkmcnt(0)
	v_mfma_f32_32x32x16_bf16 v[64:79], v[230:233], v[124:127], v[64:79]
	v_mfma_f32_32x32x16_bf16 v[80:95], v[214:217], v[124:127], v[80:95]
	ds_read_b128 v[214:217], v206 offset:32768
	ds_read_b128 v[230:233], v208 offset:40960
	s_waitcnt lgkmcnt(0)
	v_mfma_f32_32x32x16_bf16 v[64:79], v[230:233], v[112:115], v[64:79]
	v_mfma_f32_32x32x16_bf16 v[80:95], v[214:217], v[112:115], v[80:95]
	ds_read_b128 v[214:217], v207 offset:32768
	ds_read_b128 v[230:233], v209 offset:40960
	s_waitcnt lgkmcnt(0)
	v_mfma_f32_32x32x16_bf16 v[64:79], v[230:233], v[120:123], v[64:79]
	v_exp_f32_e32 v231, v238
	v_exp_f32_e32 v238, v221
	v_add_f32_e32 v221, 0, v160
	v_add_f32_e32 v221, v175, v221
	v_add_f32_e32 v221, v161, v221
	v_add_f32_e32 v221, v174, v221
	v_add_f32_e32 v221, v162, v221
	v_add_f32_e32 v221, v173, v221
	v_add_f32_e32 v221, v163, v221
	v_add_f32_e32 v221, v172, v221
	v_add_f32_e32 v221, v164, v221
	v_add_f32_e32 v221, v171, v221
	v_add_f32_e32 v221, v165, v221
	v_add_f32_e32 v221, v170, v221
	v_mfma_f32_32x32x16_bf16 v[80:95], v[214:217], v[120:123], v[80:95]
	v_exp_f32_e32 v214, v240
	v_add_f32_e32 v221, v166, v221
	v_exp_f32_e32 v215, v241
	v_add_f32_e32 v221, v169, v221
	v_exp_f32_e32 v216, v242
	v_add_f32_e32 v221, v167, v221
	v_exp_f32_e32 v217, v243
	v_add_f32_e32 v221, v168, v221
	v_exp_f32_e32 v230, v244
	v_add_f32_e32 v221, v214, v221
	v_add_f32_e32 v221, v215, v221
	v_add_f32_e32 v221, v216, v221
	v_add_f32_e32 v221, v217, v221
	v_add_f32_e32 v221, v230, v221
	v_add_f32_e32 v221, v223, v221
	v_add_f32_e32 v221, v224, v221
	v_exp_f32_e32 v232, v239
	v_add_f32_e32 v221, v225, v221
	v_exp_f32_e32 v233, v222
	v_add_f32_e32 v221, v226, v221
	v_add_f32_e32 v221, v227, v221
	v_add_f32_e32 v221, v231, v221
	v_add_f32_e32 v221, v232, v221
	v_add_f32_e32 v221, v233, v221
	v_add_f32_e32 v221, v234, v221
	v_add_f32_e32 v221, v235, v221
	v_add_f32_e32 v221, v238, v221
	v_mov_b32_e32 v222, v221
	v_cvt_pk_bf16_f32 v160, v160, v175
	v_cvt_pk_bf16_f32 v161, v161, v174
	v_cvt_pk_bf16_f32 v162, v162, v173
	v_cvt_pk_bf16_f32 v163, v163, v172
	v_cvt_pk_bf16_f32 v164, v164, v171
	v_cvt_pk_bf16_f32 v165, v165, v170
	v_cvt_pk_bf16_f32 v166, v166, v169
	v_cvt_pk_bf16_f32 v167, v167, v168
	v_cvt_pk_bf16_f32 v168, v214, v215
	v_cvt_pk_bf16_f32 v169, v216, v217
	v_cvt_pk_bf16_f32 v170, v230, v223
	v_cvt_pk_bf16_f32 v171, v224, v225
	v_cvt_pk_bf16_f32 v172, v226, v227
	v_cvt_pk_bf16_f32 v173, v231, v232
	v_cvt_pk_bf16_f32 v174, v233, v234
	v_cvt_pk_bf16_f32 v175, v235, v238
	s_nop 1
	v_permlane32_swap_b32_e32 v221, v222
	v_permlane32_swap_b32_e32 v160, v162
	v_permlane32_swap_b32_e32 v161, v163
	s_cmp_ge_i32 s28, s30
	s_cbranch_scc1 .LBB0_1102
	s_ashr_i32 s15, s14, 31
	s_mul_i32 s2, s14, 0x1400
	s_mul_hi_i32 s3, s14, 0x1400
	s_add_u32 s2, s12, s2
	s_addc_u32 s3, s13, s3
	s_lshl_b64 s[34:35], s[14:15], 9
	s_add_u32 s34, s10, s34
	v_lshl_add_u64 v[128:129], v[212:213], 1, s[2:3]
	s_addc_u32 s35, s11, s35
	v_add_co_u32_e32 v132, vcc, 0x28000, v128
	v_lshl_add_u64 v[136:137], v[176:177], 1, s[34:35]
	s_nop 0
	v_addc_co_u32_e32 v133, vcc, 0, v129, vcc
	v_add_co_u32_e32 v140, vcc, 0x4000, v136
	global_load_dwordx4 v[128:131], v[128:129], off offset:2560
	s_nop 0
	global_load_dwordx4 v[132:135], v[132:133], off offset:2560
	v_addc_co_u32_e32 v141, vcc, 0, v137, vcc
	global_load_dwordx4 v[136:139], v[136:137], off
	s_nop 0
	global_load_dwordx4 v[140:143], v[140:141], off
.LBB0_1102:
	ds_read_b64_tr_b16 v[214:215], v188 offset:0
	ds_read_b64_tr_b16 v[216:217], v188 offset:0x800
	ds_read_b64_tr_b16 v[224:225], v188 offset:0x200
	ds_read_b64_tr_b16 v[226:227], v188 offset:0xa00
	ds_read_b64_tr_b16 v[230:231], v188 offset:0x400
	ds_read_b64_tr_b16 v[232:233], v188 offset:0xc00
	ds_read_b64_tr_b16 v[238:239], v188 offset:0x600
	ds_read_b64_tr_b16 v[240:241], v188 offset:0xe00
	s_waitcnt lgkmcnt(6)
	s_nop 0
	v_mfma_f32_32x32x16_bf16 v[0:15], v[160:163], v[214:217], v[0:15]
	ds_read_b64_tr_b16 v[214:215], v188 offset:0x1000
	ds_read_b64_tr_b16 v[216:217], v188 offset:0x1800
	v_permlane32_swap_b32_e32 v164, v166
	v_permlane32_swap_b32_e32 v165, v167
	s_waitcnt lgkmcnt(6)
	v_mfma_f32_32x32x16_bf16 v[48:63], v[160:163], v[224:227], v[48:63]
	ds_read_b64_tr_b16 v[224:225], v188 offset:0x1200
	ds_read_b64_tr_b16 v[226:227], v188 offset:0x1a00
	v_permlane32_swap_b32_e32 v168, v170
	v_permlane32_swap_b32_e32 v169, v171
	s_waitcnt lgkmcnt(6)
	v_mfma_f32_32x32x16_bf16 v[32:47], v[160:163], v[230:233], v[32:47]
	ds_read_b64_tr_b16 v[230:231], v188 offset:0x1400
	ds_read_b64_tr_b16 v[232:233], v188 offset:0x1c00
	v_permlane32_swap_b32_e32 v172, v174
	v_permlane32_swap_b32_e32 v173, v175
	s_waitcnt lgkmcnt(6)
	v_mfma_f32_32x32x16_bf16 v[16:31], v[160:163], v[238:241], v[16:31]
	ds_read_b64_tr_b16 v[238:239], v188 offset:0x1600
	ds_read_b64_tr_b16 v[240:241], v188 offset:0x1e00
	s_waitcnt lgkmcnt(6)
	v_mfma_f32_32x32x16_bf16 v[0:15], v[164:167], v[214:217], v[0:15]
	ds_read_b64_tr_b16 v[214:215], v188 offset:0x2000
	ds_read_b64_tr_b16 v[216:217], v188 offset:0x2800
	v_max_f32_e32 v160, v81, v81
	v_max_f32_e32 v161, v80, v80
	v_max_f32_e32 v160, v161, v160
	v_max3_f32 v160, v160, v82, v83
	v_max3_f32 v160, v160, v84, v85
	v_max3_f32 v160, v160, v86, v87
	v_max3_f32 v160, v160, v88, v89
	v_max3_f32 v160, v160, v90, v91
	s_waitcnt lgkmcnt(6)
	v_mfma_f32_32x32x16_bf16 v[48:63], v[164:167], v[224:227], v[48:63]
	ds_read_b64_tr_b16 v[224:225], v188 offset:0x2200
	ds_read_b64_tr_b16 v[226:227], v188 offset:0x2a00
	s_waitcnt lgkmcnt(6)
	v_mfma_f32_32x32x16_bf16 v[32:47], v[164:167], v[230:233], v[32:47]
	ds_read_b64_tr_b16 v[230:231], v188 offset:0x2400
	ds_read_b64_tr_b16 v[232:233], v188 offset:0x2c00
	v_max3_f32 v160, v160, v92, v93
	v_max3_f32 v160, v160, v94, v95
	v_max3_f32 v160, v160, v64, v65
	v_max3_f32 v160, v160, v66, v67
	v_max3_f32 v160, v160, v68, v69
	v_max3_f32 v160, v160, v70, v71
	v_max3_f32 v160, v160, v72, v73
	v_max3_f32 v160, v160, v74, v75
	s_waitcnt lgkmcnt(6)
	v_mfma_f32_32x32x16_bf16 v[16:31], v[164:167], v[238:241], v[16:31]
	ds_read_b64_tr_b16 v[238:239], v188 offset:0x2600
	ds_read_b64_tr_b16 v[240:241], v188 offset:0x2e00
	s_waitcnt lgkmcnt(6)
	v_mfma_f32_32x32x16_bf16 v[0:15], v[168:171], v[214:217], v[0:15]
	ds_read_b64_tr_b16 v[214:215], v188 offset:0x3000
	ds_read_b64_tr_b16 v[216:217], v188 offset:0x3800
	v_max3_f32 v160, v160, v76, v77
	v_max3_f32 v160, v160, v78, v79
	v_mov_b32_e32 v161, v160
	s_nop 1
	v_permlane32_swap_b32_e32 v160, v161
	v_max_f32_e32 v161, v161, v161
	v_max_f32_e32 v160, v160, v160
	v_max_f32_e32 v160, v160, v161
	s_waitcnt lgkmcnt(6)
	v_mfma_f32_32x32x16_bf16 v[48:63], v[168:171], v[224:227], v[48:63]
	ds_read_b64_tr_b16 v[224:225], v188 offset:0x3200
	ds_read_b64_tr_b16 v[226:227], v188 offset:0x3a00
	s_waitcnt lgkmcnt(6)
	v_mfma_f32_32x32x16_bf16 v[32:47], v[168:171], v[230:233], v[32:47]
	ds_read_b64_tr_b16 v[230:231], v188 offset:0x3400
	ds_read_b64_tr_b16 v[232:233], v188 offset:0x3c00
	v_sub_f32_e32 v161, v160, v220
	v_cmp_ge_f32_e32 vcc, s90, v161
	v_max_f32_e32 v161, v220, v220
	v_max_f32_e32 v161, v161, v160
	v_sub_f32_e32 v160, v220, v161
	v_mul_f32_e32 v160, 0x3e0293ee, v160
	v_exp_f32_e32 v160, v160
	s_cmp_eq_u64 vcc, exec
	s_cselect_b64 s[38:39], -1, 0
	s_waitcnt lgkmcnt(6)
	v_mfma_f32_32x32x16_bf16 v[16:31], v[168:171], v[238:241], v[16:31]
	ds_read_b64_tr_b16 v[238:239], v188 offset:0x3600
	ds_read_b64_tr_b16 v[240:241], v188 offset:0x3e00
	s_waitcnt lgkmcnt(6)
	v_mfma_f32_32x32x16_bf16 v[0:15], v[172:175], v[214:217], v[0:15]
	s_waitcnt lgkmcnt(0)
	s_barrier
	v_mfma_f32_32x32x16_bf16 v[48:63], v[172:175], v[224:227], v[48:63]
	s_waitcnt vmcnt(4)
	v_cndmask_b32_e64 v160, v160, 1.0, s[38:39]
	v_cmp_gt_f32_e32 vcc, 1.0, v160
	s_waitcnt vmcnt(3)
	ds_write_b128 v190, v[144:147] offset:16384
	s_waitcnt vmcnt(2)
	ds_write_b128 v191, v[148:151] offset:16384
	v_mfma_f32_32x32x16_bf16 v[32:47], v[172:175], v[230:233], v[32:47]
	s_waitcnt vmcnt(1)
	ds_write_b128 v192, v[152:155] offset:49152
	s_waitcnt vmcnt(0)
	ds_write_b128 v193, v[156:159] offset:49152
	v_mfma_f32_32x32x16_bf16 v[16:31], v[172:175], v[238:241], v[16:31]
	s_cbranch_vccz .LBB0_1106
	s_and_saveexec_b64 s[2:3], s[36:37]
	ds_write_b32 v186, v160 offset:128
	s_or_b64 exec, exec, s[2:3]
	s_waitcnt lgkmcnt(0)
	v_add_u32_e32 v156, s27, v185
	ds_read_b128 v[144:147], v156 offset:224
	ds_read_b128 v[148:151], v156 offset:192
	ds_read_b128 v[152:155], v156 offset:160
	ds_read_b128 v[156:159], v156 offset:128
	s_waitcnt lgkmcnt(3)
	v_pk_mul_f32 v[12:13], v[12:13], v[144:145]
	s_waitcnt lgkmcnt(2)
	v_pk_mul_f32 v[8:9], v[8:9], v[148:149]
	s_waitcnt lgkmcnt(1)
	v_pk_mul_f32 v[4:5], v[4:5], v[152:153]
	v_pk_mul_f32 v[14:15], v[14:15], v[146:147]
	v_pk_mul_f32 v[10:11], v[10:11], v[150:151]
	v_pk_mul_f32 v[6:7], v[6:7], v[154:155]
	s_waitcnt lgkmcnt(0)
	v_pk_mul_f32 v[2:3], v[2:3], v[158:159]
	v_pk_mul_f32 v[0:1], v[0:1], v[156:157]
	v_pk_mul_f32 v[60:61], v[60:61], v[144:145]
	v_pk_mul_f32 v[56:57], v[56:57], v[148:149]
	v_pk_mul_f32 v[52:53], v[52:53], v[152:153]
	v_pk_mul_f32 v[62:63], v[62:63], v[146:147]
	v_pk_mul_f32 v[58:59], v[58:59], v[150:151]
	v_pk_mul_f32 v[54:55], v[54:55], v[154:155]
	v_pk_mul_f32 v[50:51], v[50:51], v[158:159]
	v_pk_mul_f32 v[48:49], v[48:49], v[156:157]
	v_pk_mul_f32 v[44:45], v[44:45], v[144:145]
	v_pk_mul_f32 v[40:41], v[40:41], v[148:149]
	v_pk_mul_f32 v[36:37], v[36:37], v[152:153]
	v_pk_mul_f32 v[46:47], v[46:47], v[146:147]
	v_pk_mul_f32 v[42:43], v[42:43], v[150:151]
	v_pk_mul_f32 v[38:39], v[38:39], v[154:155]
	v_pk_mul_f32 v[34:35], v[34:35], v[158:159]
	v_pk_mul_f32 v[32:33], v[32:33], v[156:157]
	v_pk_mul_f32 v[28:29], v[28:29], v[144:145]
	v_pk_mul_f32 v[24:25], v[24:25], v[148:149]
	v_pk_mul_f32 v[20:21], v[20:21], v[152:153]
	v_pk_mul_f32 v[30:31], v[30:31], v[146:147]
	v_pk_mul_f32 v[26:27], v[26:27], v[150:151]
	v_pk_mul_f32 v[22:23], v[22:23], v[154:155]
	v_pk_mul_f32 v[18:19], v[18:19], v[158:159]
	v_pk_mul_f32 v[16:17], v[16:17], v[156:157]

.LBB0_1135:
	ds_read_b128 v[64:67], v194 offset:57344
	ds_read_b128 v[68:71], v212 offset:57344
	ds_read_b128 v[214:217], v197 offset:57344
	ds_read_b128 v[230:233], v211 offset:57344
	v_add_f32_e32 v164, 0, v165
	v_add_f32_e32 v164, v224, v164
	s_waitcnt lgkmcnt(3)
	v_mfma_f32_32x32x16_bf16 v[80:95], v[64:67], v[140:143], 0
	v_add_f32_e32 v164, v166, v164
	v_add_f32_e32 v164, v225, v164
	v_add_f32_e32 v164, v223, v164
	v_add_f32_e32 v164, v226, v164
	v_add_f32_e32 v164, v167, v164
	v_add_f32_e32 v164, v222, v164
	v_add_f32_e32 v164, v172, v164
	s_waitcnt lgkmcnt(2)
	v_mfma_f32_32x32x16_bf16 v[64:79], v[68:71], v[140:143], 0
	v_add_f32_e32 v164, v174, v164
	v_add_f32_e32 v164, v173, v164
	v_add_f32_e32 v164, v175, v164
	v_exp_f32_e32 v158, v158
	v_add_f32_e32 v164, v160, v164
	v_exp_f32_e32 v159, v159
	v_add_f32_e32 v164, v162, v164
	s_waitcnt lgkmcnt(1)
	v_mfma_f32_32x32x16_bf16 v[80:95], v[214:217], v[136:139], v[80:95]
	v_exp_f32_e32 v156, v156
	v_add_f32_e32 v164, v161, v164
	v_exp_f32_e32 v157, v157
	v_add_f32_e32 v164, v163, v164
	v_exp_f32_e32 v152, v152
	v_add_f32_e32 v164, v158, v164
	v_exp_f32_e32 v153, v153
	s_waitcnt lgkmcnt(0)
	v_mfma_f32_32x32x16_bf16 v[64:79], v[230:233], v[136:139], v[64:79]
	ds_read_b128 v[214:217], v196 offset:57344
	ds_read_b128 v[230:233], v210 offset:57344
	v_add_f32_e32 v164, v159, v164
	v_exp_f32_e32 v148, v148
	v_add_f32_e32 v164, v156, v164
	v_exp_f32_e32 v149, v149
	v_add_f32_e32 v164, v157, v164
	v_exp_f32_e32 v146, v146
	s_waitcnt lgkmcnt(1)
	v_mfma_f32_32x32x16_bf16 v[80:95], v[214:217], v[132:135], v[80:95]
	v_add_f32_e32 v164, v152, v164
	v_exp_f32_e32 v147, v147
	v_add_f32_e32 v164, v153, v164
	v_exp_f32_e32 v154, v154
	v_add_f32_e32 v164, v148, v164
	v_exp_f32_e32 v155, v155
	v_add_f32_e32 v164, v149, v164
	s_waitcnt lgkmcnt(0)
	v_mfma_f32_32x32x16_bf16 v[64:79], v[230:233], v[132:135], v[64:79]
	ds_read_b128 v[214:217], v195 offset:57344
	ds_read_b128 v[230:233], v209 offset:57344
	v_exp_f32_e32 v150, v150
	v_add_f32_e32 v164, v146, v164
	v_exp_f32_e32 v151, v151
	v_add_f32_e32 v164, v147, v164
	v_exp_f32_e32 v144, v144
	v_add_f32_e32 v164, v154, v164
	s_waitcnt lgkmcnt(1)
	v_mfma_f32_32x32x16_bf16 v[80:95], v[214:217], v[128:131], v[80:95]
	v_exp_f32_e32 v145, v145
	v_add_f32_e32 v164, v155, v164
	v_add_f32_e32 v164, v150, v164
	v_add_f32_e32 v164, v151, v164
	v_add_f32_e32 v164, v144, v164
	v_add_f32_e32 v219, v145, v164
	v_mov_b32_e32 v220, v219
	s_waitcnt lgkmcnt(0)
	v_mfma_f32_32x32x16_bf16 v[64:79], v[230:233], v[128:131], v[64:79]
	ds_read_b128 v[214:217], v193 offset:57344
	ds_read_b128 v[230:233], v208 offset:57344
	v_permlane32_swap_b32_e32 v219, v220
	s_waitcnt lgkmcnt(1)
	v_mfma_f32_32x32x16_bf16 v[80:95], v[214:217], v[124:127], v[80:95]
	s_waitcnt lgkmcnt(0)
	v_mfma_f32_32x32x16_bf16 v[64:79], v[230:233], v[124:127], v[64:79]
	ds_read_b128 v[214:217], v192 offset:57344
	ds_read_b128 v[230:233], v206 offset:57344
	s_waitcnt lgkmcnt(1)
	v_mfma_f32_32x32x16_bf16 v[80:95], v[214:217], v[120:123], v[80:95]
	s_waitcnt lgkmcnt(0)
	v_mfma_f32_32x32x16_bf16 v[64:79], v[230:233], v[120:123], v[64:79]
	ds_read_b128 v[214:217], v186 offset:57344
	ds_read_b128 v[230:233], v205 offset:57344
	s_waitcnt lgkmcnt(1)
	v_mfma_f32_32x32x16_bf16 v[80:95], v[214:217], v[116:119], v[80:95]
	s_waitcnt lgkmcnt(0)
	v_mfma_f32_32x32x16_bf16 v[64:79], v[230:233], v[116:119], v[64:79]
	ds_read_b128 v[214:217], v189 offset:57344
	ds_read_b128 v[230:233], v204 offset:57344
	s_waitcnt lgkmcnt(1)
	v_mfma_f32_32x32x16_bf16 v[80:95], v[214:217], v[112:115], v[80:95]
	s_waitcnt lgkmcnt(0)
	v_mfma_f32_32x32x16_bf16 v[64:79], v[230:233], v[112:115], v[64:79]
	ds_read_b128 v[214:217], v190 offset:57344
	ds_read_b128 v[230:233], v203 offset:57344
	s_waitcnt lgkmcnt(1)
	v_mfma_f32_32x32x16_bf16 v[80:95], v[214:217], v[108:111], v[80:95]
	s_waitcnt lgkmcnt(0)
	v_mfma_f32_32x32x16_bf16 v[64:79], v[230:233], v[108:111], v[64:79]
	ds_read_b128 v[214:217], v188 offset:57344
	ds_read_b128 v[230:233], v202 offset:57344
	s_waitcnt lgkmcnt(1)
	v_mfma_f32_32x32x16_bf16 v[80:95], v[214:217], v[104:107], v[80:95]
	s_waitcnt lgkmcnt(0)
	v_mfma_f32_32x32x16_bf16 v[64:79], v[230:233], v[104:107], v[64:79]
	ds_read_b128 v[214:217], v199 offset:57344
	ds_read_b128 v[230:233], v201 offset:57344
	s_waitcnt lgkmcnt(1)
	v_mfma_f32_32x32x16_bf16 v[80:95], v[214:217], v[100:103], v[80:95]
	s_waitcnt lgkmcnt(0)
	v_mfma_f32_32x32x16_bf16 v[64:79], v[230:233], v[100:103], v[64:79]
	ds_read_b128 v[214:217], v198 offset:57344
	ds_read_b128 v[230:233], v200 offset:57344
	v_cvt_pk_bf16_f32 v164, v165, v224
	v_cvt_pk_bf16_f32 v165, v166, v225
	v_cvt_pk_bf16_f32 v166, v223, v226
	v_cvt_pk_bf16_f32 v167, v167, v222
	s_nop 0
	v_permlane32_swap_b32_e32 v164, v166
	s_waitcnt lgkmcnt(1)
	v_mfma_f32_32x32x16_bf16 v[80:95], v[214:217], v[96:99], v[80:95]
	v_cvt_pk_bf16_f32 v214, v172, v174
	v_cvt_pk_bf16_f32 v215, v173, v175
	v_cvt_pk_bf16_f32 v216, v160, v162
	v_cvt_pk_bf16_f32 v217, v161, v163
	v_cvt_pk_bf16_f32 v222, v158, v159
	v_cvt_pk_bf16_f32 v223, v156, v157
	v_cvt_pk_bf16_f32 v224, v152, v153
	s_waitcnt lgkmcnt(0)
	v_mfma_f32_32x32x16_bf16 v[64:79], v[230:233], v[96:99], v[64:79]
	v_cvt_pk_bf16_f32 v225, v148, v149
	v_cvt_pk_bf16_f32 v230, v146, v147
	v_cvt_pk_bf16_f32 v231, v154, v155
	v_cvt_pk_bf16_f32 v232, v150, v151
	v_cvt_pk_bf16_f32 v233, v144, v145
	v_permlane32_swap_b32_e32 v165, v167
	v_lshl_add_u64 v[172:173], s[44:45], 0, v[170:171]
	s_mov_b32 s2, 0x4bf80000
	v_add_co_u32_e32 v148, vcc, s2, v172
	s_mov_b32 s2, 0x4bfa0000
	s_nop 0
	v_addc_co_u32_e32 v149, vcc, 0, v173, vcc
	v_add_co_u32_e32 v152, vcc, s2, v172
	v_lshl_add_u64 v[174:175], s[44:45], 0, v[168:169]
	s_nop 0
	v_addc_co_u32_e32 v153, vcc, 0, v173, vcc
	global_load_dwordx4 v[144:147], v[148:149], off offset:256
	s_nop 0
	global_load_dwordx4 v[148:151], v[148:149], off
	s_nop 0
	global_load_dwordx4 v[156:159], v[152:153], off offset:256
	s_nop 0
	global_load_dwordx4 v[152:155], v[152:153], off
	s_mov_b32 s2, 0x45404000
	v_add_co_u32_e32 v160, vcc, s2, v174
	s_nop 1
	v_addc_co_u32_e32 v161, vcc, 0, v175, vcc
	global_load_dwordx4 v[160:163], v[160:161], off
	ds_read_b64_tr_b16 v[238:239], v182 offset:0
	ds_read_b64_tr_b16 v[240:241], v182 offset:0x800
	ds_read_b64_tr_b16 v[242:243], v182 offset:0x200
	ds_read_b64_tr_b16 v[244:245], v182 offset:0xa00
	ds_read_b64_tr_b16 v[246:247], v182 offset:0x400
	ds_read_b64_tr_b16 v[248:249], v182 offset:0xc00
	ds_read_b64_tr_b16 v[250:251], v182 offset:0x600
	ds_read_b64_tr_b16 v[252:253], v182 offset:0xe00
	s_waitcnt lgkmcnt(6)
	s_nop 0
	v_mfma_f32_32x32x16_bf16 v[0:15], v[164:167], v[238:241], v[0:15]
	ds_read_b64_tr_b16 v[238:239], v182 offset:0x1000
	ds_read_b64_tr_b16 v[240:241], v182 offset:0x1800
	v_permlane32_swap_b32_e32 v214, v216
	v_permlane32_swap_b32_e32 v215, v217
	s_waitcnt lgkmcnt(6)
	v_mfma_f32_32x32x16_bf16 v[48:63], v[164:167], v[242:245], v[48:63]
	ds_read_b64_tr_b16 v[242:243], v182 offset:0x1200
	ds_read_b64_tr_b16 v[244:245], v182 offset:0x1a00
	v_permlane32_swap_b32_e32 v222, v224
	v_permlane32_swap_b32_e32 v223, v225
	s_waitcnt lgkmcnt(6)
	v_mfma_f32_32x32x16_bf16 v[32:47], v[164:167], v[246:249], v[32:47]
	ds_read_b64_tr_b16 v[246:247], v182 offset:0x1400
	ds_read_b64_tr_b16 v[248:249], v182 offset:0x1c00
	v_permlane32_swap_b32_e32 v230, v232
	v_permlane32_swap_b32_e32 v231, v233
	s_waitcnt lgkmcnt(6)
	v_mfma_f32_32x32x16_bf16 v[16:31], v[164:167], v[250:253], v[16:31]
	ds_read_b64_tr_b16 v[250:251], v182 offset:0x1600
	ds_read_b64_tr_b16 v[252:253], v182 offset:0x1e00
	s_waitcnt lgkmcnt(6)
	v_mfma_f32_32x32x16_bf16 v[0:15], v[214:217], v[238:241], v[0:15]
	ds_read_b64_tr_b16 v[238:239], v182 offset:0x2000
	ds_read_b64_tr_b16 v[240:241], v182 offset:0x2800
	v_max_f32_e32 v164, v81, v81
	v_max_f32_e32 v165, v80, v80
	v_max_f32_e32 v164, v165, v164
	v_max3_f32 v164, v164, v82, v83
	v_max3_f32 v164, v164, v84, v85
	v_max3_f32 v164, v164, v86, v87
	v_max3_f32 v164, v164, v88, v89
	v_max3_f32 v164, v164, v90, v91
	s_waitcnt lgkmcnt(6)
	v_mfma_f32_32x32x16_bf16 v[48:63], v[214:217], v[242:245], v[48:63]
	ds_read_b64_tr_b16 v[242:243], v182 offset:0x2200
	ds_read_b64_tr_b16 v[244:245], v182 offset:0x2a00
	s_waitcnt lgkmcnt(6)
	v_mfma_f32_32x32x16_bf16 v[32:47], v[214:217], v[246:249], v[32:47]
	ds_read_b64_tr_b16 v[246:247], v182 offset:0x2400
	ds_read_b64_tr_b16 v[248:249], v182 offset:0x2c00
	v_max3_f32 v164, v164, v92, v93
	v_max3_f32 v164, v164, v94, v95
	v_max3_f32 v164, v164, v64, v65
	v_max3_f32 v164, v164, v66, v67
	v_max3_f32 v164, v164, v68, v69
	v_max3_f32 v164, v164, v70, v71
	v_max3_f32 v164, v164, v72, v73
	v_max3_f32 v164, v164, v74, v75
	s_waitcnt lgkmcnt(6)
	v_mfma_f32_32x32x16_bf16 v[16:31], v[214:217], v[250:253], v[16:31]
	ds_read_b64_tr_b16 v[250:251], v182 offset:0x2600
	ds_read_b64_tr_b16 v[252:253], v182 offset:0x2e00
	s_waitcnt lgkmcnt(6)
	v_mfma_f32_32x32x16_bf16 v[0:15], v[222:225], v[238:241], v[0:15]
	ds_read_b64_tr_b16 v[238:239], v182 offset:0x3000
	ds_read_b64_tr_b16 v[240:241], v182 offset:0x3800
	v_max3_f32 v164, v164, v76, v77
	v_max3_f32 v164, v164, v78, v79
	v_mov_b32_e32 v165, v164
	s_nop 1
	v_permlane32_swap_b32_e32 v164, v165
	v_max_f32_e32 v165, v165, v165
	v_max_f32_e32 v164, v164, v164
	v_max_f32_e32 v164, v164, v165
	s_waitcnt lgkmcnt(6)
	v_mfma_f32_32x32x16_bf16 v[48:63], v[222:225], v[242:245], v[48:63]
	ds_read_b64_tr_b16 v[242:243], v182 offset:0x3200
	ds_read_b64_tr_b16 v[244:245], v182 offset:0x3a00
	s_waitcnt lgkmcnt(6)
	v_mfma_f32_32x32x16_bf16 v[32:47], v[222:225], v[246:249], v[32:47]
	ds_read_b64_tr_b16 v[246:247], v182 offset:0x3400
	ds_read_b64_tr_b16 v[248:249], v182 offset:0x3c00
	v_sub_f32_e32 v165, v164, v207
	v_cmp_ge_f32_e32 vcc, s46, v165
	v_max_f32_e32 v165, v207, v207
	v_max_f32_e32 v164, v165, v164
	v_sub_f32_e32 v165, v207, v164
	v_mul_f32_e32 v165, 0x3dd53b94, v165
	v_exp_f32_e32 v165, v165
	s_cmp_eq_u64 vcc, exec
	s_cselect_b64 s[38:39], -1, 0
	s_waitcnt lgkmcnt(6)
	v_mfma_f32_32x32x16_bf16 v[16:31], v[222:225], v[250:253], v[16:31]
	ds_read_b64_tr_b16 v[250:251], v182 offset:0x3600
	ds_read_b64_tr_b16 v[252:253], v182 offset:0x3e00
	s_waitcnt lgkmcnt(6)
	v_mfma_f32_32x32x16_bf16 v[0:15], v[230:233], v[238:241], v[0:15]
	s_waitcnt lgkmcnt(0)
	s_barrier
	v_mfma_f32_32x32x16_bf16 v[48:63], v[230:233], v[242:245], v[48:63]
	s_waitcnt vmcnt(0)
	v_cndmask_b32_e64 v221, v165, 1.0, s[38:39]
	v_cmp_gt_f32_e32 vcc, 1.0, v221
	s_waitcnt vmcnt(4)
	ds_write_b128 v183, v[144:147]
	s_waitcnt vmcnt(2)
	ds_write_b128 v184, v[156:159]
	v_mfma_f32_32x32x16_bf16 v[32:47], v[230:233], v[246:249], v[32:47]
	ds_write_b128 v185, v[148:151] offset:32768
	s_waitcnt vmcnt(1)
	ds_write_b128 v187, v[152:155] offset:32768
	s_waitcnt vmcnt(0)
	ds_write_b128 v191, v[160:163] offset:32768
	v_mfma_f32_32x32x16_bf16 v[16:31], v[230:233], v[250:253], v[16:31]
	s_cbranch_vccz .LBB0_1139
	s_and_saveexec_b64 s[2:3], s[36:37]
	ds_write_b32 v179, v221 offset:128
	s_or_b64 exec, exec, s[2:3]
	s_waitcnt lgkmcnt(0)
	v_add_u32_e32 v156, s14, v178
	ds_read_b128 v[144:147], v156 offset:224
	ds_read_b128 v[148:151], v156 offset:192
	ds_read_b128 v[152:155], v156 offset:160
	ds_read_b128 v[156:159], v156 offset:128
	s_waitcnt lgkmcnt(3)
	v_pk_mul_f32 v[12:13], v[12:13], v[144:145]
	s_waitcnt lgkmcnt(2)
	v_pk_mul_f32 v[8:9], v[8:9], v[148:149]
	s_waitcnt lgkmcnt(1)
	v_pk_mul_f32 v[4:5], v[4:5], v[152:153]
	v_pk_mul_f32 v[14:15], v[14:15], v[146:147]
	v_pk_mul_f32 v[10:11], v[10:11], v[150:151]
	v_pk_mul_f32 v[6:7], v[6:7], v[154:155]
	s_waitcnt lgkmcnt(0)
	v_pk_mul_f32 v[2:3], v[2:3], v[158:159]
	v_pk_mul_f32 v[0:1], v[0:1], v[156:157]
	v_pk_mul_f32 v[60:61], v[60:61], v[144:145]
	v_pk_mul_f32 v[56:57], v[56:57], v[148:149]
	v_pk_mul_f32 v[52:53], v[52:53], v[152:153]
	v_pk_mul_f32 v[62:63], v[62:63], v[146:147]
	v_pk_mul_f32 v[58:59], v[58:59], v[150:151]
	v_pk_mul_f32 v[54:55], v[54:55], v[154:155]
	v_pk_mul_f32 v[50:51], v[50:51], v[158:159]
	v_pk_mul_f32 v[48:49], v[48:49], v[156:157]
	v_pk_mul_f32 v[44:45], v[44:45], v[144:145]
	v_pk_mul_f32 v[40:41], v[40:41], v[148:149]
	v_pk_mul_f32 v[36:37], v[36:37], v[152:153]
	v_pk_mul_f32 v[46:47], v[46:47], v[146:147]
	v_pk_mul_f32 v[42:43], v[42:43], v[150:151]
	v_pk_mul_f32 v[38:39], v[38:39], v[154:155]
	v_pk_mul_f32 v[34:35], v[34:35], v[158:159]
	v_pk_mul_f32 v[32:33], v[32:33], v[156:157]
	v_pk_mul_f32 v[28:29], v[28:29], v[144:145]
	v_pk_mul_f32 v[24:25], v[24:25], v[148:149]
	v_pk_mul_f32 v[20:21], v[20:21], v[152:153]
	v_pk_mul_f32 v[30:31], v[30:31], v[146:147]
	v_pk_mul_f32 v[26:27], v[26:27], v[150:151]
	v_pk_mul_f32 v[22:23], v[22:23], v[154:155]
	v_pk_mul_f32 v[18:19], v[18:19], v[158:159]
	v_pk_mul_f32 v[16:17], v[16:17], v[156:157]
.LBB0_1139:
	v_cndmask_b32_e64 v207, v164, v207, s[38:39]
	v_mul_f32_e32 v160, 0xbdd53b94, v207
	v_fmamk_f32 v80, v80, 0x3dd53b94, v160
	v_fmamk_f32 v81, v81, 0x3dd53b94, v160
	v_fmamk_f32 v82, v82, 0x3dd53b94, v160
	v_fmamk_f32 v83, v83, 0x3dd53b94, v160
	v_fmamk_f32 v84, v84, 0x3dd53b94, v160
	v_fmamk_f32 v85, v85, 0x3dd53b94, v160
	v_fmamk_f32 v86, v86, 0x3dd53b94, v160
	v_fmamk_f32 v87, v87, 0x3dd53b94, v160
	v_fmamk_f32 v88, v88, 0x3dd53b94, v160
	v_fmamk_f32 v89, v89, 0x3dd53b94, v160
	v_fmamk_f32 v90, v90, 0x3dd53b94, v160
	v_fmamk_f32 v91, v91, 0x3dd53b94, v160
	v_fmamk_f32 v92, v92, 0x3dd53b94, v160
	v_fmamk_f32 v93, v93, 0x3dd53b94, v160
	v_fmamk_f32 v94, v94, 0x3dd53b94, v160
	v_fmamk_f32 v95, v95, 0x3dd53b94, v160
	v_fmamk_f32 v227, v68, 0x3dd53b94, v160
	v_fmamk_f32 v164, v71, 0x3dd53b94, v160
	v_fmamk_f32 v165, v72, 0x3dd53b94, v160
	v_fmamk_f32 v238, v77, 0x3dd53b94, v160
	v_fmamk_f32 v223, v64, 0x3dd53b94, v160
	v_fmamk_f32 v224, v65, 0x3dd53b94, v160
	v_fmamk_f32 v225, v66, 0x3dd53b94, v160
	v_fmamk_f32 v226, v67, 0x3dd53b94, v160
	v_fmamk_f32 v162, v69, 0x3dd53b94, v160
	v_fmamk_f32 v163, v70, 0x3dd53b94, v160
	v_fmamk_f32 v166, v73, 0x3dd53b94, v160
	v_fmamk_f32 v167, v74, 0x3dd53b94, v160
	v_fmamk_f32 v222, v75, 0x3dd53b94, v160
	v_fmamk_f32 v161, v76, 0x3dd53b94, v160
	v_exp_f32_e32 v157, v80
	v_exp_f32_e32 v159, v81
	v_exp_f32_e32 v155, v82
	v_exp_f32_e32 v158, v83
	v_exp_f32_e32 v154, v84
	v_exp_f32_e32 v156, v85
	v_exp_f32_e32 v152, v86
	v_exp_f32_e32 v153, v87
	v_exp_f32_e32 v149, v88
	v_exp_f32_e32 v151, v89
	v_exp_f32_e32 v148, v90
	v_exp_f32_e32 v150, v91
	v_exp_f32_e32 v145, v92
	v_exp_f32_e32 v147, v93
	v_exp_f32_e32 v144, v94
	v_exp_f32_e32 v146, v95
	v_fmamk_f32 v239, v78, 0x3dd53b94, v160
	v_fmac_f32_e32 v160, 0x3dd53b94, v79
	s_waitcnt lgkmcnt(0)
	s_barrier
	ds_read_b128 v[64:67], v194 offset:32768
	ds_read_b128 v[68:71], v194 offset:45056
	ds_read_b128 v[214:217], v197 offset:32768
	ds_read_b128 v[230:233], v197 offset:45056
	v_exp_f32_e32 v223, v223
	v_exp_f32_e32 v224, v224
	s_waitcnt lgkmcnt(3)
	v_mfma_f32_32x32x16_bf16 v[80:95], v[64:67], v[140:143], 0
	v_exp_f32_e32 v225, v225
	v_exp_f32_e32 v226, v226
	v_exp_f32_e32 v162, v162
	v_exp_f32_e32 v163, v163
	v_exp_f32_e32 v234, v167
	v_exp_f32_e32 v235, v222
	v_exp_f32_e32 v161, v161
	s_waitcnt lgkmcnt(2)
	v_mfma_f32_32x32x16_bf16 v[64:79], v[68:71], v[140:143], 0
	v_exp_f32_e32 v240, v238
	v_exp_f32_e32 v239, v239
	v_exp_f32_e32 v160, v160
	s_waitcnt lgkmcnt(0)
	v_mfma_f32_32x32x16_bf16 v[64:79], v[230:233], v[136:139], v[64:79]
	v_mfma_f32_32x32x16_bf16 v[80:95], v[214:217], v[136:139], v[80:95]
	ds_read_b128 v[214:217], v196 offset:32768
	ds_read_b128 v[230:233], v196 offset:45056
	s_waitcnt lgkmcnt(0)
	v_mfma_f32_32x32x16_bf16 v[64:79], v[230:233], v[132:135], v[64:79]
	v_mfma_f32_32x32x16_bf16 v[80:95], v[214:217], v[132:135], v[80:95]
	ds_read_b128 v[214:217], v195 offset:32768
	ds_read_b128 v[230:233], v195 offset:45056
	s_waitcnt lgkmcnt(0)
	v_mfma_f32_32x32x16_bf16 v[64:79], v[230:233], v[128:131], v[64:79]
	v_mfma_f32_32x32x16_bf16 v[80:95], v[214:217], v[128:131], v[80:95]
	ds_read_b128 v[214:217], v193 offset:32768
	ds_read_b128 v[230:233], v193 offset:45056
	s_waitcnt lgkmcnt(0)
	v_mfma_f32_32x32x16_bf16 v[64:79], v[230:233], v[124:127], v[64:79]
	v_mfma_f32_32x32x16_bf16 v[80:95], v[214:217], v[124:127], v[80:95]
	ds_read_b128 v[214:217], v192 offset:32768
	ds_read_b128 v[230:233], v192 offset:45056
	s_waitcnt lgkmcnt(0)
	v_mfma_f32_32x32x16_bf16 v[64:79], v[230:233], v[120:123], v[64:79]
	v_mfma_f32_32x32x16_bf16 v[80:95], v[214:217], v[120:123], v[80:95]
	ds_read_b128 v[214:217], v186 offset:32768
	ds_read_b128 v[230:233], v186 offset:45056
	s_waitcnt lgkmcnt(0)
	v_mfma_f32_32x32x16_bf16 v[64:79], v[230:233], v[116:119], v[64:79]
	v_mfma_f32_32x32x16_bf16 v[80:95], v[214:217], v[116:119], v[80:95]
	ds_read_b128 v[214:217], v189 offset:32768
	ds_read_b128 v[230:233], v189 offset:45056
	s_waitcnt lgkmcnt(0)
	v_mfma_f32_32x32x16_bf16 v[64:79], v[230:233], v[112:115], v[64:79]
	v_mfma_f32_32x32x16_bf16 v[80:95], v[214:217], v[112:115], v[80:95]
	ds_read_b128 v[214:217], v190 offset:32768
	ds_read_b128 v[230:233], v190 offset:45056
	s_waitcnt lgkmcnt(0)
	v_mfma_f32_32x32x16_bf16 v[64:79], v[230:233], v[108:111], v[64:79]
	v_mfma_f32_32x32x16_bf16 v[80:95], v[214:217], v[108:111], v[80:95]
	ds_read_b128 v[214:217], v188 offset:32768
	ds_read_b128 v[230:233], v188 offset:45056
	s_waitcnt lgkmcnt(0)
	v_mfma_f32_32x32x16_bf16 v[64:79], v[230:233], v[104:107], v[64:79]
	v_mfma_f32_32x32x16_bf16 v[80:95], v[214:217], v[104:107], v[80:95]
	ds_read_b128 v[214:217], v199 offset:32768
	ds_read_b128 v[230:233], v199 offset:45056
	s_waitcnt lgkmcnt(0)
	v_mfma_f32_32x32x16_bf16 v[64:79], v[230:233], v[100:103], v[64:79]
	v_mfma_f32_32x32x16_bf16 v[80:95], v[214:217], v[100:103], v[80:95]
	ds_read_b128 v[214:217], v198 offset:32768
	ds_read_b128 v[230:233], v198 offset:45056
	s_waitcnt lgkmcnt(0)
	v_mfma_f32_32x32x16_bf16 v[64:79], v[230:233], v[96:99], v[64:79]
	v_exp_f32_e32 v231, v164
	v_add_f32_e32 v164, 0, v157
	v_add_f32_e32 v164, v159, v164
	v_add_f32_e32 v164, v155, v164
	v_add_f32_e32 v164, v158, v164
	v_add_f32_e32 v164, v154, v164
	v_add_f32_e32 v164, v156, v164
	v_add_f32_e32 v164, v152, v164
	v_add_f32_e32 v164, v153, v164
	v_add_f32_e32 v164, v149, v164
	v_add_f32_e32 v164, v151, v164
	v_add_f32_e32 v164, v148, v164
	v_add_f32_e32 v164, v150, v164
	v_add_f32_e32 v164, v145, v164
	v_add_f32_e32 v164, v147, v164
	v_add_f32_e32 v164, v144, v164
	v_add_f32_e32 v164, v146, v164
	v_exp_f32_e32 v230, v227
	v_add_f32_e32 v164, v223, v164
	v_add_f32_e32 v164, v224, v164
	v_add_f32_e32 v164, v225, v164
	v_add_f32_e32 v164, v226, v164
	v_exp_f32_e32 v232, v165
	v_add_f32_e32 v164, v230, v164
	v_exp_f32_e32 v233, v166
	v_add_f32_e32 v164, v162, v164
	v_add_f32_e32 v164, v163, v164
	v_add_f32_e32 v164, v231, v164
	v_add_f32_e32 v164, v232, v164
	v_add_f32_e32 v164, v233, v164
	v_mfma_f32_32x32x16_bf16 v[80:95], v[214:217], v[96:99], v[80:95]
	v_add_f32_e32 v164, v234, v164
	v_add_f32_e32 v164, v235, v164
	v_add_f32_e32 v164, v161, v164
	v_add_f32_e32 v164, v240, v164
	v_add_f32_e32 v164, v239, v164
	v_add_f32_e32 v227, v160, v164
	v_mov_b32_e32 v238, v227
	v_cvt_pk_bf16_f32 v164, v157, v159
	v_cvt_pk_bf16_f32 v165, v155, v158
	v_cvt_pk_bf16_f32 v166, v154, v156
	v_cvt_pk_bf16_f32 v167, v152, v153
	s_nop 1
	v_permlane32_swap_b32_e32 v227, v238
	v_permlane32_swap_b32_e32 v164, v166
	v_permlane32_swap_b32_e32 v165, v167
	v_cvt_pk_bf16_f32 v214, v149, v151
	v_cvt_pk_bf16_f32 v215, v148, v150
	v_cvt_pk_bf16_f32 v216, v145, v147
	v_cvt_pk_bf16_f32 v217, v144, v146
	v_cvt_pk_bf16_f32 v222, v223, v224
	v_cvt_pk_bf16_f32 v223, v225, v226
	v_cvt_pk_bf16_f32 v224, v230, v162
	v_cvt_pk_bf16_f32 v225, v163, v231
	v_cvt_pk_bf16_f32 v230, v232, v233
	v_cvt_pk_bf16_f32 v231, v234, v235
	v_cvt_pk_bf16_f32 v232, v161, v240
	v_cvt_pk_bf16_f32 v233, v239, v160
	s_nop 0
	s_mov_b32 s2, 0x4bfc0000
	v_add_co_u32_e32 v148, vcc, s2, v172
	s_mov_b32 s2, 0x4bfe0000
	s_nop 0
	v_addc_co_u32_e32 v149, vcc, 0, v173, vcc
	v_add_co_u32_e32 v152, vcc, s2, v172
	s_mov_b32 s2, 0x45406000
	s_nop 0
	v_addc_co_u32_e32 v153, vcc, 0, v173, vcc
	global_load_dwordx4 v[144:147], v[148:149], off offset:256
	s_nop 0
	global_load_dwordx4 v[148:151], v[148:149], off
	s_nop 0
	global_load_dwordx4 v[156:159], v[152:153], off offset:256
	s_nop 0
	global_load_dwordx4 v[152:155], v[152:153], off
	v_add_co_u32_e32 v160, vcc, s2, v174
	s_nop 1
	v_addc_co_u32_e32 v161, vcc, 0, v175, vcc
	global_load_dwordx4 v[160:163], v[160:161], off
	ds_read_b64_tr_b16 v[172:173], v181 offset:0
	ds_read_b64_tr_b16 v[174:175], v181 offset:0x800
	ds_read_b64_tr_b16 v[240:241], v181 offset:0x200
	ds_read_b64_tr_b16 v[242:243], v181 offset:0xa00
	ds_read_b64_tr_b16 v[244:245], v181 offset:0x400
	ds_read_b64_tr_b16 v[246:247], v181 offset:0xc00
	ds_read_b64_tr_b16 v[248:249], v181 offset:0x600
	ds_read_b64_tr_b16 v[250:251], v181 offset:0xe00
	s_waitcnt lgkmcnt(6)
	s_nop 0
	v_mfma_f32_32x32x16_bf16 v[0:15], v[164:167], v[172:175], v[0:15]
	ds_read_b64_tr_b16 v[172:173], v181 offset:0x1000
	ds_read_b64_tr_b16 v[174:175], v181 offset:0x1800
	v_permlane32_swap_b32_e32 v214, v216
	v_permlane32_swap_b32_e32 v215, v217
	s_waitcnt lgkmcnt(6)
	v_mfma_f32_32x32x16_bf16 v[48:63], v[164:167], v[240:243], v[48:63]
	ds_read_b64_tr_b16 v[240:241], v181 offset:0x1200
	ds_read_b64_tr_b16 v[242:243], v181 offset:0x1a00
	v_permlane32_swap_b32_e32 v222, v224
	v_permlane32_swap_b32_e32 v223, v225
	s_waitcnt lgkmcnt(6)
	v_mfma_f32_32x32x16_bf16 v[32:47], v[164:167], v[244:247], v[32:47]
	ds_read_b64_tr_b16 v[244:245], v181 offset:0x1400
	ds_read_b64_tr_b16 v[246:247], v181 offset:0x1c00
	v_permlane32_swap_b32_e32 v230, v232
	v_permlane32_swap_b32_e32 v231, v233
	s_waitcnt lgkmcnt(6)
	v_mfma_f32_32x32x16_bf16 v[16:31], v[164:167], v[248:251], v[16:31]
	ds_read_b64_tr_b16 v[248:249], v181 offset:0x1600
	ds_read_b64_tr_b16 v[250:251], v181 offset:0x1e00
	s_waitcnt lgkmcnt(6)
	v_mfma_f32_32x32x16_bf16 v[0:15], v[214:217], v[172:175], v[0:15]
	ds_read_b64_tr_b16 v[172:173], v181 offset:0x2000
	ds_read_b64_tr_b16 v[174:175], v181 offset:0x2800
	v_max_f32_e32 v164, v81, v81
	v_max_f32_e32 v165, v80, v80
	v_max_f32_e32 v164, v165, v164
	v_max3_f32 v164, v164, v82, v83
	v_max3_f32 v164, v164, v84, v85
	v_max3_f32 v164, v164, v86, v87
	v_max3_f32 v164, v164, v88, v89
	v_max3_f32 v164, v164, v90, v91
	s_waitcnt lgkmcnt(6)
	v_mfma_f32_32x32x16_bf16 v[48:63], v[214:217], v[240:243], v[48:63]
	ds_read_b64_tr_b16 v[240:241], v181 offset:0x2200
	ds_read_b64_tr_b16 v[242:243], v181 offset:0x2a00
	s_waitcnt lgkmcnt(6)
	v_mfma_f32_32x32x16_bf16 v[32:47], v[214:217], v[244:247], v[32:47]
	ds_read_b64_tr_b16 v[244:245], v181 offset:0x2400
	ds_read_b64_tr_b16 v[246:247], v181 offset:0x2c00
	v_max3_f32 v164, v164, v92, v93
	v_max3_f32 v164, v164, v94, v95
	v_max3_f32 v164, v164, v64, v65
	v_max3_f32 v164, v164, v66, v67
	v_max3_f32 v164, v164, v68, v69
	v_max3_f32 v164, v164, v70, v71
	v_max3_f32 v164, v164, v72, v73
	v_max3_f32 v164, v164, v74, v75
	s_waitcnt lgkmcnt(6)
	v_mfma_f32_32x32x16_bf16 v[16:31], v[214:217], v[248:251], v[16:31]
	ds_read_b64_tr_b16 v[248:249], v181 offset:0x2600
	ds_read_b64_tr_b16 v[250:251], v181 offset:0x2e00
	s_waitcnt lgkmcnt(6)
	v_mfma_f32_32x32x16_bf16 v[0:15], v[222:225], v[172:175], v[0:15]
	ds_read_b64_tr_b16 v[172:173], v181 offset:0x3000
	ds_read_b64_tr_b16 v[174:175], v181 offset:0x3800
	v_max3_f32 v164, v164, v76, v77
	v_max3_f32 v164, v164, v78, v79
	v_mov_b32_e32 v165, v164
	s_nop 1
	v_permlane32_swap_b32_e32 v164, v165
	v_max_f32_e32 v165, v165, v165
	v_max_f32_e32 v164, v164, v164
	v_max_f32_e32 v164, v164, v165
	s_waitcnt lgkmcnt(6)
	v_mfma_f32_32x32x16_bf16 v[48:63], v[222:225], v[240:243], v[48:63]
	ds_read_b64_tr_b16 v[240:241], v181 offset:0x3200
	ds_read_b64_tr_b16 v[242:243], v181 offset:0x3a00
	s_waitcnt lgkmcnt(6)
	v_mfma_f32_32x32x16_bf16 v[32:47], v[222:225], v[244:247], v[32:47]
	ds_read_b64_tr_b16 v[244:245], v181 offset:0x3400
	ds_read_b64_tr_b16 v[246:247], v181 offset:0x3c00
	v_sub_f32_e32 v165, v164, v207
	v_cmp_ge_f32_e32 vcc, s46, v165
	v_max_f32_e32 v165, v207, v207
	v_max_f32_e32 v165, v165, v164
	v_sub_f32_e32 v164, v207, v165
	v_mul_f32_e32 v164, 0x3dd53b94, v164
	v_exp_f32_e32 v164, v164
	s_cmp_eq_u64 vcc, exec
	s_cselect_b64 s[38:39], -1, 0
	s_waitcnt lgkmcnt(6)
	v_mfma_f32_32x32x16_bf16 v[16:31], v[222:225], v[248:251], v[16:31]
	ds_read_b64_tr_b16 v[248:249], v181 offset:0x3600
	ds_read_b64_tr_b16 v[250:251], v181 offset:0x3e00
	s_waitcnt lgkmcnt(6)
	v_mfma_f32_32x32x16_bf16 v[0:15], v[230:233], v[172:175], v[0:15]
	s_waitcnt lgkmcnt(0)
	s_barrier
	v_mfma_f32_32x32x16_bf16 v[48:63], v[230:233], v[240:243], v[48:63]
	s_waitcnt vmcnt(0)
	v_cndmask_b32_e64 v164, v164, 1.0, s[38:39]
	v_cmp_gt_f32_e32 vcc, 1.0, v164
	s_waitcnt vmcnt(4)
	ds_write_b128 v183, v[144:147] offset:16384
	s_waitcnt vmcnt(2)
	ds_write_b128 v184, v[156:159] offset:16384
	v_mfma_f32_32x32x16_bf16 v[32:47], v[230:233], v[244:247], v[32:47]
	ds_write_b128 v185, v[148:151] offset:57344
	s_waitcnt vmcnt(1)
	ds_write_b128 v187, v[152:155] offset:57344
	s_waitcnt vmcnt(0)
	ds_write_b128 v191, v[160:163] offset:57344
	v_mfma_f32_32x32x16_bf16 v[16:31], v[230:233], v[248:251], v[16:31]
	s_cbranch_vccz .LBB0_1143
	s_and_saveexec_b64 s[2:3], s[36:37]
	ds_write_b32 v179, v164 offset:128
	s_or_b64 exec, exec, s[2:3]
	s_waitcnt lgkmcnt(0)
	v_add_u32_e32 v156, s14, v178
	ds_read_b128 v[144:147], v156 offset:224
	ds_read_b128 v[148:151], v156 offset:192
	ds_read_b128 v[152:155], v156 offset:160
	ds_read_b128 v[156:159], v156 offset:128
	s_waitcnt lgkmcnt(3)
	v_pk_mul_f32 v[12:13], v[12:13], v[144:145]
	s_waitcnt lgkmcnt(2)
	v_pk_mul_f32 v[8:9], v[8:9], v[148:149]
	s_waitcnt lgkmcnt(1)
	v_pk_mul_f32 v[4:5], v[4:5], v[152:153]
	v_pk_mul_f32 v[14:15], v[14:15], v[146:147]
	v_pk_mul_f32 v[10:11], v[10:11], v[150:151]
	v_pk_mul_f32 v[6:7], v[6:7], v[154:155]
	s_waitcnt lgkmcnt(0)
	v_pk_mul_f32 v[2:3], v[2:3], v[158:159]
	v_pk_mul_f32 v[0:1], v[0:1], v[156:157]
	v_pk_mul_f32 v[60:61], v[60:61], v[144:145]
	v_pk_mul_f32 v[56:57], v[56:57], v[148:149]
	v_pk_mul_f32 v[52:53], v[52:53], v[152:153]
	v_pk_mul_f32 v[62:63], v[62:63], v[146:147]
	v_pk_mul_f32 v[58:59], v[58:59], v[150:151]
	v_pk_mul_f32 v[54:55], v[54:55], v[154:155]
	v_pk_mul_f32 v[50:51], v[50:51], v[158:159]
	v_pk_mul_f32 v[48:49], v[48:49], v[156:157]
	v_pk_mul_f32 v[44:45], v[44:45], v[144:145]
	v_pk_mul_f32 v[40:41], v[40:41], v[148:149]
	v_pk_mul_f32 v[36:37], v[36:37], v[152:153]
	v_pk_mul_f32 v[46:47], v[46:47], v[146:147]
	v_pk_mul_f32 v[42:43], v[42:43], v[150:151]
	v_pk_mul_f32 v[38:39], v[38:39], v[154:155]
	v_pk_mul_f32 v[34:35], v[34:35], v[158:159]
	v_pk_mul_f32 v[32:33], v[32:33], v[156:157]
	v_pk_mul_f32 v[28:29], v[28:29], v[144:145]
	v_pk_mul_f32 v[24:25], v[24:25], v[148:149]
	v_pk_mul_f32 v[20:21], v[20:21], v[152:153]
	v_pk_mul_f32 v[30:31], v[30:31], v[146:147]
	v_pk_mul_f32 v[26:27], v[26:27], v[150:151]
	v_pk_mul_f32 v[22:23], v[22:23], v[154:155]
	v_pk_mul_f32 v[18:19], v[18:19], v[158:159]
	v_pk_mul_f32 v[16:17], v[16:17], v[156:157]
